# stagprio
# speedup vs baseline: 1.0094x; 1.0094x over previous
.Lsrt_loop_b:
	s_setprio 1
	v_mfma_f32_16x16x32_bf16 v[30:33], v[60:63], v[64:67], v[30:33]
	v_mfma_f32_16x16x32_bf16 v[14:17], v[68:71], v[64:67], v[14:17]
	v_mfma_f32_16x16x32_bf16 v[26:29], v[60:63], v[88:91], v[26:29]
	v_mfma_f32_16x16x32_bf16 v[10:13], v[68:71], v[88:91], v[10:13]
	v_mfma_f32_16x16x32_bf16 v[22:25], v[60:63], v[92:95], v[22:25]
	v_mfma_f32_16x16x32_bf16 v[6:9], v[68:71], v[92:95], v[6:9]
	v_mfma_f32_16x16x32_bf16 v[18:21], v[60:63], v[96:99], v[18:21]
	v_mfma_f32_16x16x32_bf16 v[2:5], v[68:71], v[96:99], v[2:5]
	v_mfma_f32_16x16x32_bf16 v[30:33], v[100:103], v[104:107], v[30:33]
	v_mfma_f32_16x16x32_bf16 v[14:17], v[108:111], v[104:107], v[14:17]
	v_mfma_f32_16x16x32_bf16 v[26:29], v[100:103], v[112:115], v[26:29]
	v_mfma_f32_16x16x32_bf16 v[10:13], v[108:111], v[112:115], v[10:13]
	v_mfma_f32_16x16x32_bf16 v[22:25], v[100:103], v[116:119], v[22:25]
	v_mfma_f32_16x16x32_bf16 v[6:9], v[108:111], v[116:119], v[6:9]
	v_mfma_f32_16x16x32_bf16 v[18:21], v[100:103], v[120:123], v[18:21]
	v_mfma_f32_16x16x32_bf16 v[2:5], v[108:111], v[120:123], v[2:5]
	s_setprio 0
	s_waitcnt vmcnt(4)
	ds_write_b128 v57, v[46:49]
	ds_write_b128 v57, v[42:45] offset:16
	ds_write_b128 v57, v[38:41] offset:20480
	ds_write_b128 v57, v[34:37] offset:20496
	ds_read_b128 v[176:179], v59 offset:61440
	ds_read_b128 v[180:183], v58 offset:40960
	ds_read_b128 v[184:187], v59 offset:64000
	ds_read_b128 v[188:191], v58 offset:43520
	ds_read_b128 v[192:195], v58 offset:46080
	ds_read_b128 v[196:199], v58 offset:48640
	ds_read_b128 v[200:203], v59 offset:61504
	ds_read_b128 v[204:207], v58 offset:41024
	ds_read_b128 v[208:211], v59 offset:64064
	ds_read_b128 v[224:227], v58 offset:43584
	ds_read_b128 v[228:231], v58 offset:46144
	ds_read_b128 v[232:235], v58 offset:48704
	s_add_i32 s14, s6, 4
	s_add_i32 s22, s64, -1
	s_min_u32 s14, s14, s22
	s_lshl_b32 s22, s14, 7
	s_waitcnt lgkmcnt(12)
	v_lshl_add_u64 v[124:125], v[50:51], 0, s[22:23]
	v_lshl_add_u64 v[126:127], v[52:53], 0, s[22:23]
	global_load_dwordx4 v[46:49], v[124:125], off
	global_load_dwordx4 v[42:45], v[124:125], off offset:16
	global_load_dwordx4 v[38:41], v[126:127], off
	global_load_dwordx4 v[34:37], v[126:127], off offset:16
	s_waitcnt lgkmcnt(0)
	s_barrier
	s_setprio 1
	v_mfma_f32_16x16x32_bf16 v[30:33], v[176:179], v[180:183], v[30:33]
	v_mfma_f32_16x16x32_bf16 v[14:17], v[184:187], v[180:183], v[14:17]
	v_mfma_f32_16x16x32_bf16 v[26:29], v[176:179], v[188:191], v[26:29]
	v_mfma_f32_16x16x32_bf16 v[10:13], v[184:187], v[188:191], v[10:13]
	v_mfma_f32_16x16x32_bf16 v[22:25], v[176:179], v[192:195], v[22:25]
	v_mfma_f32_16x16x32_bf16 v[6:9], v[184:187], v[192:195], v[6:9]
	v_mfma_f32_16x16x32_bf16 v[18:21], v[176:179], v[196:199], v[18:21]
	v_mfma_f32_16x16x32_bf16 v[2:5], v[184:187], v[196:199], v[2:5]
	v_mfma_f32_16x16x32_bf16 v[30:33], v[200:203], v[204:207], v[30:33]
	v_mfma_f32_16x16x32_bf16 v[14:17], v[208:211], v[204:207], v[14:17]
	v_mfma_f32_16x16x32_bf16 v[26:29], v[200:203], v[224:227], v[26:29]
	v_mfma_f32_16x16x32_bf16 v[10:13], v[208:211], v[224:227], v[10:13]
	v_mfma_f32_16x16x32_bf16 v[22:25], v[200:203], v[228:231], v[22:25]
	v_mfma_f32_16x16x32_bf16 v[6:9], v[208:211], v[228:231], v[6:9]
	v_mfma_f32_16x16x32_bf16 v[18:21], v[200:203], v[232:235], v[18:21]
	v_mfma_f32_16x16x32_bf16 v[2:5], v[208:211], v[232:235], v[2:5]
	s_setprio 0
	s_waitcnt vmcnt(4)
	ds_write_b128 v57, v[84:87] offset:40960
	ds_write_b128 v57, v[80:83] offset:40976
	ds_write_b128 v57, v[76:79] offset:61440
	ds_write_b128 v57, v[72:75] offset:61456
	ds_read_b128 v[60:63], v59 offset:20480
	ds_read_b128 v[64:67], v58
	ds_read_b128 v[68:71], v59 offset:23040
	ds_read_b128 v[88:91], v58 offset:2560
	ds_read_b128 v[92:95], v58 offset:5120
	ds_read_b128 v[96:99], v58 offset:7680
	ds_read_b128 v[100:103], v59 offset:20544
	ds_read_b128 v[104:107], v58 offset:64
	ds_read_b128 v[108:111], v59 offset:23104
	ds_read_b128 v[112:115], v58 offset:2624
	ds_read_b128 v[116:119], v58 offset:5184
	ds_read_b128 v[120:123], v58 offset:7744
	s_add_i32 s14, s6, 5
	s_add_i32 s22, s64, -1
	s_min_u32 s14, s14, s22
	s_lshl_b32 s22, s14, 7
	s_waitcnt lgkmcnt(12)
	v_lshl_add_u64 v[124:125], v[50:51], 0, s[22:23]
	v_lshl_add_u64 v[126:127], v[52:53], 0, s[22:23]
	global_load_dwordx4 v[84:87], v[124:125], off
	global_load_dwordx4 v[80:83], v[124:125], off offset:16
	global_load_dwordx4 v[76:79], v[126:127], off
	global_load_dwordx4 v[72:75], v[126:127], off offset:16
	s_waitcnt lgkmcnt(0)
	s_barrier
	s_add_i32 s6, s6, 2
	s_cmp_lt_u32 s6, s64
	s_cbranch_scc1 .Lsrt_loop_b
